# in-projection GEMM: epilogues no longer barrier-aligned between the two wave halves (leading half stores while trailing half finishes its last MMA)
# speedup vs baseline: 1.0006x; 1.0006x over previous
; #define PG8_STAGE(bufoff, gbase, voff) do { _Pragma("unroll") for (int _i = 0; _i < 2; ++_i) \
;         __builtin_amdgcn_global_load_lds((const unsigned*)((const char*)(gbase) + (voff)[_i]), (LAS unsigned*)(lds + (bufoff) + ldsw + _i * 8192), 16, 0, 0); } while (0)
; #define PG8_LDA(dst, b, h) do { _Pragma("unroll") for (int m = 0; m < 4; ++m) _Pragma("unroll") for (int k = 0; k < 2; ++k) dst[m][k] = *(const LAS bf16x8*)(lds + PG8_SA(b, h) + aoff + m * 2048 + k * 1024); } while (0)
; #define PG8_LDB(dst, b, h) do { _Pragma("unroll") for (int n = 0; n < 2; ++n) _Pragma("unroll") for (int k = 0; k < 2; ++k) dst[n][k] = *(const LAS bf16x8*)(lds + PG8_SB(b, h) + boff + n * 2048 + k * 1024); } while (0)
; #define PG8_MMA(ai, bj, At, Bt) do { __builtin_amdgcn_s_setprio(1); _Pragma("unroll") for (int m = 0; m < 4; ++m) _Pragma("unroll") for (int n = 0; n < 2; ++n) _Pragma("unroll") for (int k = 0; k < 2; ++k) \
;         acc[ai][bj][m][n] = __builtin_amdgcn_mfma_f32_16x16x32_bf16(Bt[n][k], At[m][k], acc[ai][bj][m][n], 0, 0, 0); __builtin_amdgcn_s_setprio(0); } while (0)
; #define PG8_WAIT_V(n) asm volatile("s_waitcnt vmcnt(" #n ")" ::: "memory")
; #define PG8_WAIT_L(n) asm volatile("s_waitcnt lgkmcnt(" #n ")" ::: "memory")
; #define PG8_BAR __builtin_amdgcn_s_barrier()
; #define PG8_SCHED __builtin_amdgcn_sched_barrier(0)
; template <class Epi, bool PERMA = false, bool DUAL = false, bool ALIGN_EPI = true, bool SP2 = true>
; __device__ __forceinline__ void gemm_phase(LAS unsigned char* lds, const Gemm g, const StaticOrder& S, const Epi& E) {
;     ...
;             const bool last = (t == nt - 2);
;             const char* a1 = cA + (size_t)(t + 1) * kstep;
;             const char* a2 = last ? nA : cA + (size_t)(t + 2) * kstep; const char* b2 = last ? nB : cB + (size_t)(t + 2) * kstep;
;             const char* a3 = a2 + kstep; const char* b3 = b2 + kstep;
;             if constexpr (SP2) {
;             PG8_LDB(B0, 0, 0); PG8_LDB(B1, 0, 1); PG8_SCHED; PG8_LDA(At, 0, 0); PG8_STAGE(PG8_SA(1, 1), a1 + hstepA, voffA);
;             PG8_WAIT_V(8); PG8_WAIT_L(0); PG8_BAR; PG8_MMA(0, 0, At, B0); PG8_MMA(0, 1, At, B1); PG8_BAR; PG8_SCHED;
;             PG8_LDA(At, 0, 1); PG8_STAGE(PG8_SB(0, 0), b2, voffB); PG8_STAGE(PG8_SB(0, 1), b2 + hstepB, voffB); PG8_STAGE(PG8_SA(0, 0), a2, voffA);
.LBB0_130:
	s_add_u32 s16, s14, 0xfff80080
	s_addc_u32 s17, s15, -1
	s_add_i32 s38, 0, 0x10000
	s_cmp_eq_u32 s37, 28
	s_cselect_b32 s19, s9, s17
	s_cselect_b32 s18, s33, s16
	s_cselect_b32 s17, s7, s36
	s_cselect_b32 s16, s34, s35
	s_add_i32 s40, 0, 0x14000
	v_add_u32_e32 v156, s38, v141
	v_add_u32_e32 v172, s40, v141
	ds_read_b128 v[144:147], v156
	ds_read_b128 v[148:151], v156 offset:1024
	ds_read_b128 v[152:155], v156 offset:2048
	ds_read_b128 v[156:159], v156 offset:3072
	ds_read_b128 v[160:163], v172
	ds_read_b128 v[164:167], v172 offset:1024
	ds_read_b128 v[168:171], v172 offset:2048
	ds_read_b128 v[172:175], v172 offset:3072
	v_lshl_add_u64 v[222:223], s[14:15], 0, v[136:137]
	s_add_i32 m0, s21, 0xc000
	ds_read_b128 v[176:179], v143
	ds_read_b128 v[180:183], v143 offset:1024
	ds_read_b128 v[184:187], v143 offset:2048
	ds_read_b128 v[188:191], v143 offset:3072
	ds_read_b128 v[206:209], v143 offset:4096
	ds_read_b128 v[210:213], v143 offset:5120
	ds_read_b128 v[214:217], v143 offset:6144
	ds_read_b128 v[218:221], v143 offset:7168
	global_load_lds_dwordx4 v[222:223], off
	v_lshl_add_u64 v[222:223], s[14:15], 0, v[138:139]
	s_add_i32 m0, s21, 0xe000
	s_nop 0
	global_load_lds_dwordx4 v[222:223], off
	s_waitcnt vmcnt(8)
	s_waitcnt lgkmcnt(0)
	s_barrier
	s_waitcnt lgkmcnt(0)
	v_mfma_f32_16x16x32_bf16 v[124:127], v[144:147], v[176:179], v[124:127]
	v_mfma_f32_16x16x32_bf16 v[120:123], v[152:155], v[176:179], v[120:123]
	v_mfma_f32_16x16x32_bf16 v[116:119], v[144:147], v[184:187], v[116:119]
	v_mfma_f32_16x16x32_bf16 v[108:111], v[152:155], v[184:187], v[108:111]
	v_mfma_f32_16x16x32_bf16 v[100:103], v[144:147], v[206:209], v[100:103]
	v_mfma_f32_16x16x32_bf16 v[92:95], v[152:155], v[206:209], v[92:95]
	v_mfma_f32_16x16x32_bf16 v[84:87], v[144:147], v[214:217], v[84:87]
	v_mfma_f32_16x16x32_bf16 v[76:79], v[152:155], v[214:217], v[76:79]
	v_mfma_f32_16x16x32_bf16 v[124:127], v[148:151], v[180:183], v[124:127]
	v_mfma_f32_16x16x32_bf16 v[120:123], v[156:159], v[180:183], v[120:123]
	v_mfma_f32_16x16x32_bf16 v[116:119], v[148:151], v[188:191], v[116:119]
	v_mfma_f32_16x16x32_bf16 v[108:111], v[156:159], v[188:191], v[108:111]
	v_mfma_f32_16x16x32_bf16 v[100:103], v[148:151], v[210:213], v[100:103]
	v_mfma_f32_16x16x32_bf16 v[92:95], v[156:159], v[210:213], v[92:95]
	v_mfma_f32_16x16x32_bf16 v[84:87], v[148:151], v[218:221], v[84:87]
	v_mfma_f32_16x16x32_bf16 v[76:79], v[156:159], v[218:221], v[76:79]
	v_mfma_f32_16x16x32_bf16 v[112:115], v[160:163], v[176:179], v[112:115]
	v_mfma_f32_16x16x32_bf16 v[104:107], v[168:171], v[176:179], v[104:107]
	v_mfma_f32_16x16x32_bf16 v[96:99], v[160:163], v[184:187], v[96:99]
	v_mfma_f32_16x16x32_bf16 v[88:91], v[168:171], v[184:187], v[88:91]
	v_mfma_f32_16x16x32_bf16 v[80:83], v[160:163], v[206:209], v[80:83]
	v_mfma_f32_16x16x32_bf16 v[72:75], v[168:171], v[206:209], v[72:75]
	v_mfma_f32_16x16x32_bf16 v[68:71], v[160:163], v[214:217], v[68:71]
	v_mfma_f32_16x16x32_bf16 v[64:67], v[168:171], v[214:217], v[64:67]
	v_mfma_f32_16x16x32_bf16 v[112:115], v[164:167], v[180:183], v[112:115]
	v_mfma_f32_16x16x32_bf16 v[104:107], v[172:175], v[180:183], v[104:107]
	v_mfma_f32_16x16x32_bf16 v[96:99], v[164:167], v[188:191], v[96:99]
	v_mfma_f32_16x16x32_bf16 v[88:91], v[172:175], v[188:191], v[88:91]
	v_mfma_f32_16x16x32_bf16 v[80:83], v[164:167], v[210:213], v[80:83]
	v_mfma_f32_16x16x32_bf16 v[72:75], v[172:175], v[210:213], v[72:75]
	v_mfma_f32_16x16x32_bf16 v[68:71], v[164:167], v[218:221], v[68:71]
	v_mfma_f32_16x16x32_bf16 v[64:67], v[172:175], v[218:221], v[64:67]
	s_barrier
	s_add_i32 s38, s38, s20
	v_lshl_add_u64 v[222:223], s[16:17], 0, v[132:133]
	s_mov_b32 m0, s38
	ds_read_b128 v[176:179], v143 offset:16384
	ds_read_b128 v[180:183], v143 offset:17408
	ds_read_b128 v[184:187], v143 offset:18432
	ds_read_b128 v[188:191], v143 offset:19456
	ds_read_b128 v[206:209], v143 offset:20480
	ds_read_b128 v[210:213], v143 offset:21504
	ds_read_b128 v[214:217], v143 offset:22528
	ds_read_b128 v[218:221], v143 offset:23552
	global_load_lds_dwordx4 v[222:223], off
	s_add_i32 m0, s38, 0x2000
	s_add_u32 s38, s16, 0x80000
	v_lshl_add_u64 v[224:225], s[16:17], 0, v[128:129]
	s_addc_u32 s39, s17, 0
	s_add_i32 s40, s40, s20
	global_load_lds_dwordx4 v[224:225], off
	v_lshl_add_u64 v[226:227], s[38:39], 0, v[132:133]
	s_mov_b32 m0, s40
	v_lshl_add_u64 v[228:229], s[18:19], 0, v[130:131]
	global_load_lds_dwordx4 v[226:227], off
	v_lshl_add_u64 v[226:227], s[38:39], 0, v[128:129]
	s_add_i32 m0, s40, 0x2000
	s_nop 0
	global_load_lds_dwordx4 v[226:227], off
	v_lshl_add_u64 v[226:227], s[18:19], 0, v[134:135]
	s_mov_b32 m0, s21
	s_nop 0
	global_load_lds_dwordx4 v[226:227], off
	s_mov_b32 m0, s22
	s_nop 0
	global_load_lds_dwordx4 v[228:229], off
	s_waitcnt vmcnt(8)
	s_waitcnt lgkmcnt(0)
	s_barrier
; #define PG8_STAGE(bufoff, gbase, voff) do { _Pragma("unroll") for (int _i = 0; _i < 2; ++_i) \
;         __builtin_amdgcn_global_load_lds((const unsigned*)((const char*)(gbase) + (voff)[_i]), (LAS unsigned*)(lds + (bufoff) + ldsw + _i * 8192), 16, 0, 0); } while (0)
; #define PG8_LDA(dst, b, h) do { _Pragma("unroll") for (int m = 0; m < 4; ++m) _Pragma("unroll") for (int k = 0; k < 2; ++k) dst[m][k] = *(const LAS bf16x8*)(lds + PG8_SA(b, h) + aoff + m * 2048 + k * 1024); } while (0)
; #define PG8_LDB(dst, b, h) do { _Pragma("unroll") for (int n = 0; n < 2; ++n) _Pragma("unroll") for (int k = 0; k < 2; ++k) dst[n][k] = *(const LAS bf16x8*)(lds + PG8_SB(b, h) + boff + n * 2048 + k * 1024); } while (0)
; #define PG8_MMA(ai, bj, At, Bt) do { __builtin_amdgcn_s_setprio(1); _Pragma("unroll") for (int m = 0; m < 4; ++m) _Pragma("unroll") for (int n = 0; n < 2; ++n) _Pragma("unroll") for (int k = 0; k < 2; ++k) \
;         acc[ai][bj][m][n] = __builtin_amdgcn_mfma_f32_16x16x32_bf16(Bt[n][k], At[m][k], acc[ai][bj][m][n], 0, 0, 0); __builtin_amdgcn_s_setprio(0); } while (0)
; #define PG8_WAIT_V(n) asm volatile("s_waitcnt vmcnt(" #n ")" ::: "memory")
; #define PG8_WAIT_L(n) asm volatile("s_waitcnt lgkmcnt(" #n ")" ::: "memory")
; #define PG8_BAR __builtin_amdgcn_s_barrier()
; #define PG8_SCHED __builtin_amdgcn_sched_barrier(0)
; template <class Epi, bool PERMA = false, bool DUAL = false, bool ALIGN_EPI = true, bool SP2 = true>
; __device__ __forceinline__ void gemm_phase(LAS unsigned char* lds, const Gemm g, const StaticOrder& S, const Epi& E) {
;     ...
;             PG8_WAIT_V(8); PG8_WAIT_L(0); PG8_BAR; PG8_MMA(1, 0, At, B0); PG8_MMA(1, 1, At, B1); PG8_BAR; PG8_SCHED;
;             PG8_LDB(B0, 1, 0); PG8_LDB(B1, 1, 1); PG8_SCHED; PG8_LDA(At, 1, 0); PG8_STAGE(PG8_SA(0, 1), a2 + hstepA, voffA);
;             PG8_WAIT_V(8); PG8_WAIT_L(0); PG8_BAR; PG8_MMA(0, 0, At, B0); PG8_MMA(0, 1, At, B1); PG8_BAR; PG8_SCHED;
	s_waitcnt lgkmcnt(0)
	v_mfma_f32_16x16x32_bf16 v[60:63], v[144:147], v[176:179], v[60:63]
	v_mfma_f32_16x16x32_bf16 v[56:59], v[152:155], v[176:179], v[56:59]
	v_mfma_f32_16x16x32_bf16 v[52:55], v[144:147], v[184:187], v[52:55]
	v_mfma_f32_16x16x32_bf16 v[44:47], v[152:155], v[184:187], v[44:47]
	v_mfma_f32_16x16x32_bf16 v[36:39], v[144:147], v[206:209], v[36:39]
	v_mfma_f32_16x16x32_bf16 v[28:31], v[152:155], v[206:209], v[28:31]
	v_mfma_f32_16x16x32_bf16 v[20:23], v[144:147], v[214:217], v[20:23]
	v_mfma_f32_16x16x32_bf16 v[12:15], v[152:155], v[214:217], v[12:15]
	v_mfma_f32_16x16x32_bf16 v[60:63], v[148:151], v[180:183], v[60:63]
	v_mfma_f32_16x16x32_bf16 v[56:59], v[156:159], v[180:183], v[56:59]
	v_mfma_f32_16x16x32_bf16 v[52:55], v[148:151], v[188:191], v[52:55]
	v_mfma_f32_16x16x32_bf16 v[44:47], v[156:159], v[188:191], v[44:47]
	v_mfma_f32_16x16x32_bf16 v[36:39], v[148:151], v[210:213], v[36:39]
	v_mfma_f32_16x16x32_bf16 v[28:31], v[156:159], v[210:213], v[28:31]
	v_mfma_f32_16x16x32_bf16 v[20:23], v[148:151], v[218:221], v[20:23]
	v_mfma_f32_16x16x32_bf16 v[12:15], v[156:159], v[218:221], v[12:15]
	v_mfma_f32_16x16x32_bf16 v[48:51], v[160:163], v[176:179], v[48:51]
	v_mfma_f32_16x16x32_bf16 v[40:43], v[168:171], v[176:179], v[40:43]
	v_mfma_f32_16x16x32_bf16 v[32:35], v[160:163], v[184:187], v[32:35]
	v_mfma_f32_16x16x32_bf16 v[24:27], v[168:171], v[184:187], v[24:27]
	v_mfma_f32_16x16x32_bf16 v[16:19], v[160:163], v[206:209], v[16:19]
	v_mfma_f32_16x16x32_bf16 v[8:11], v[168:171], v[206:209], v[8:11]
	v_mfma_f32_16x16x32_bf16 v[4:7], v[160:163], v[214:217], v[4:7]
	v_mfma_f32_16x16x32_bf16 v[0:3], v[168:171], v[214:217], v[0:3]
	v_mfma_f32_16x16x32_bf16 v[48:51], v[164:167], v[180:183], v[48:51]
	v_mfma_f32_16x16x32_bf16 v[40:43], v[172:175], v[180:183], v[40:43]
	v_mfma_f32_16x16x32_bf16 v[32:35], v[164:167], v[188:191], v[32:35]
	v_mfma_f32_16x16x32_bf16 v[24:27], v[172:175], v[188:191], v[24:27]
	v_mfma_f32_16x16x32_bf16 v[16:19], v[164:167], v[210:213], v[16:19]
	v_mfma_f32_16x16x32_bf16 v[8:11], v[172:175], v[210:213], v[8:11]
	v_mfma_f32_16x16x32_bf16 v[4:7], v[164:167], v[218:221], v[4:7]
	v_mfma_f32_16x16x32_bf16 v[0:3], v[172:175], v[218:221], v[0:3]
	s_barrier
	s_add_i32 s38, 0, 0x18000
	s_add_i32 s39, 0, 0x1c000
	v_add_u32_e32 v156, s38, v141
	v_add_u32_e32 v172, s39, v141
	ds_read_b128 v[144:147], v156
	ds_read_b128 v[148:151], v156 offset:1024
	ds_read_b128 v[152:155], v156 offset:2048
	ds_read_b128 v[156:159], v156 offset:3072
	ds_read_b128 v[160:163], v172
	ds_read_b128 v[164:167], v172 offset:1024
	ds_read_b128 v[168:171], v172 offset:2048
	ds_read_b128 v[172:175], v172 offset:3072
	s_add_u32 s18, s18, 0x80000
	s_addc_u32 s19, s19, 0
	s_mov_b32 m0, s23
	v_lshl_add_u64 v[238:239], s[18:19], 0, v[134:135]
	ds_read_b128 v[176:179], v143 offset:32768
	ds_read_b128 v[180:183], v143 offset:33792
	ds_read_b128 v[184:187], v143 offset:34816
	ds_read_b128 v[188:191], v143 offset:35840
	ds_read_b128 v[206:209], v143 offset:36864
	ds_read_b128 v[210:213], v143 offset:37888
	ds_read_b128 v[214:217], v143 offset:38912
	ds_read_b128 v[218:221], v143 offset:39936
	global_load_lds_dwordx4 v[238:239], off
	v_lshl_add_u64 v[238:239], s[18:19], 0, v[130:131]
	s_mov_b32 m0, s24
	s_nop 0
	global_load_lds_dwordx4 v[238:239], off
	s_waitcnt vmcnt(8)
	s_waitcnt lgkmcnt(0)
	s_barrier
	s_waitcnt lgkmcnt(0)
	v_mfma_f32_16x16x32_bf16 v[124:127], v[144:147], v[176:179], v[124:127]
	v_mfma_f32_16x16x32_bf16 v[120:123], v[152:155], v[176:179], v[120:123]
	v_mfma_f32_16x16x32_bf16 v[116:119], v[144:147], v[184:187], v[116:119]
	v_mfma_f32_16x16x32_bf16 v[108:111], v[152:155], v[184:187], v[108:111]
	v_mfma_f32_16x16x32_bf16 v[100:103], v[144:147], v[206:209], v[100:103]
	v_mfma_f32_16x16x32_bf16 v[92:95], v[152:155], v[206:209], v[92:95]
	v_mfma_f32_16x16x32_bf16 v[84:87], v[144:147], v[214:217], v[84:87]
	v_mfma_f32_16x16x32_bf16 v[76:79], v[152:155], v[214:217], v[76:79]
	v_mfma_f32_16x16x32_bf16 v[124:127], v[148:151], v[180:183], v[124:127]
	v_mfma_f32_16x16x32_bf16 v[120:123], v[156:159], v[180:183], v[120:123]
	v_mfma_f32_16x16x32_bf16 v[116:119], v[148:151], v[188:191], v[116:119]
	v_mfma_f32_16x16x32_bf16 v[108:111], v[156:159], v[188:191], v[108:111]
	v_mfma_f32_16x16x32_bf16 v[100:103], v[148:151], v[210:213], v[100:103]
	v_mfma_f32_16x16x32_bf16 v[92:95], v[156:159], v[210:213], v[92:95]
	v_mfma_f32_16x16x32_bf16 v[84:87], v[148:151], v[218:221], v[84:87]
	v_mfma_f32_16x16x32_bf16 v[76:79], v[156:159], v[218:221], v[76:79]
	v_mfma_f32_16x16x32_bf16 v[112:115], v[160:163], v[176:179], v[112:115]
	v_mfma_f32_16x16x32_bf16 v[104:107], v[168:171], v[176:179], v[104:107]
	v_mfma_f32_16x16x32_bf16 v[96:99], v[160:163], v[184:187], v[96:99]
	v_mfma_f32_16x16x32_bf16 v[88:91], v[168:171], v[184:187], v[88:91]
	v_mfma_f32_16x16x32_bf16 v[80:83], v[160:163], v[206:209], v[80:83]
	v_mfma_f32_16x16x32_bf16 v[72:75], v[168:171], v[206:209], v[72:75]
	v_mfma_f32_16x16x32_bf16 v[68:71], v[160:163], v[214:217], v[68:71]
	v_mfma_f32_16x16x32_bf16 v[64:67], v[168:171], v[214:217], v[64:67]
	v_mfma_f32_16x16x32_bf16 v[112:115], v[164:167], v[180:183], v[112:115]
	v_mfma_f32_16x16x32_bf16 v[104:107], v[172:175], v[180:183], v[104:107]
	v_mfma_f32_16x16x32_bf16 v[96:99], v[164:167], v[188:191], v[96:99]
	v_mfma_f32_16x16x32_bf16 v[88:91], v[172:175], v[188:191], v[88:91]
	v_mfma_f32_16x16x32_bf16 v[80:83], v[164:167], v[210:213], v[80:83]
	v_mfma_f32_16x16x32_bf16 v[72:75], v[172:175], v[210:213], v[72:75]
	v_mfma_f32_16x16x32_bf16 v[68:71], v[164:167], v[218:221], v[68:71]
	v_mfma_f32_16x16x32_bf16 v[64:67], v[172:175], v[218:221], v[64:67]
	s_barrier
; #define PG8_STAGE(bufoff, gbase, voff) do { _Pragma("unroll") for (int _i = 0; _i < 2; ++_i) \
;         __builtin_amdgcn_global_load_lds((const unsigned*)((const char*)(gbase) + (voff)[_i]), (LAS unsigned*)(lds + (bufoff) + ldsw + _i * 8192), 16, 0, 0); } while (0)
; #define PG8_LDA(dst, b, h) do { _Pragma("unroll") for (int m = 0; m < 4; ++m) _Pragma("unroll") for (int k = 0; k < 2; ++k) dst[m][k] = *(const LAS bf16x8*)(lds + PG8_SA(b, h) + aoff + m * 2048 + k * 1024); } while (0)
; #define PG8_MMA(ai, bj, At, Bt) do { __builtin_amdgcn_s_setprio(1); _Pragma("unroll") for (int m = 0; m < 4; ++m) _Pragma("unroll") for (int n = 0; n < 2; ++n) _Pragma("unroll") for (int k = 0; k < 2; ++k) \
;         acc[ai][bj][m][n] = __builtin_amdgcn_mfma_f32_16x16x32_bf16(Bt[n][k], At[m][k], acc[ai][bj][m][n], 0, 0, 0); __builtin_amdgcn_s_setprio(0); } while (0)
; #define PG8_WAIT_V(n) asm volatile("s_waitcnt vmcnt(" #n ")" ::: "memory")
; #define PG8_WAIT_L(n) asm volatile("s_waitcnt lgkmcnt(" #n ")" ::: "memory")
; #define PG8_BAR __builtin_amdgcn_s_barrier()
; #define PG8_SCHED __builtin_amdgcn_sched_barrier(0)
; template <class Epi, bool PERMA = false, bool DUAL = false, bool ALIGN_EPI = true, bool SP2 = true>
; __device__ __forceinline__ void gemm_phase(LAS unsigned char* lds, const Gemm g, const StaticOrder& S, const Epi& E) {
;     ...
;             PG8_LDA(At, 1, 1); PG8_STAGE(PG8_SB(1, 0), b3, voffB); PG8_STAGE(PG8_SB(1, 1), b3 + hstepB, voffB); PG8_STAGE(PG8_SA(1, 0), a3, voffA);
;             PG8_WAIT_V(8); PG8_WAIT_L(0); PG8_BAR; PG8_MMA(1, 0, At, B0); PG8_MMA(1, 1, At, B1); PG8_BAR; PG8_SCHED;
	s_add_i32 s18, s38, s20
	v_lshl_add_u64 v[222:223], v[222:223], 0, s[46:47]
	s_mov_b32 m0, s18
	ds_read_b128 v[176:179], v143 offset:49152
	ds_read_b128 v[180:183], v143 offset:50176
	ds_read_b128 v[184:187], v143 offset:51200
	ds_read_b128 v[188:191], v143 offset:52224
	ds_read_b128 v[206:209], v143 offset:53248
	ds_read_b128 v[210:213], v143 offset:54272
	ds_read_b128 v[214:217], v143 offset:55296
	ds_read_b128 v[218:221], v143 offset:56320
	global_load_lds_dwordx4 v[222:223], off
	s_add_i32 m0, s18, 0x2000
	s_add_u32 s16, s16, 0x80080
	v_lshl_add_u64 v[222:223], v[224:225], 0, s[46:47]
	s_addc_u32 s17, s17, 0
	s_add_i32 s18, s39, s20
	global_load_lds_dwordx4 v[222:223], off
	v_lshl_add_u64 v[222:223], s[16:17], 0, v[132:133]
	s_mov_b32 m0, s18
	s_nop 0
	global_load_lds_dwordx4 v[222:223], off
	v_lshl_add_u64 v[222:223], s[16:17], 0, v[128:129]
	s_add_i32 m0, s18, 0x2000
	s_nop 0
	global_load_lds_dwordx4 v[222:223], off
	v_lshl_add_u64 v[222:223], v[226:227], 0, s[46:47]
	s_mov_b32 m0, s25
	s_nop 0
	global_load_lds_dwordx4 v[222:223], off
	v_lshl_add_u64 v[222:223], v[228:229], 0, s[46:47]
	s_mov_b32 m0, s26
	s_nop 0
	global_load_lds_dwordx4 v[222:223], off
	s_waitcnt vmcnt(8)
	s_waitcnt lgkmcnt(0)
	s_barrier
	s_waitcnt lgkmcnt(0)
	v_mfma_f32_16x16x32_bf16 v[60:63], v[144:147], v[176:179], v[60:63]
	v_mfma_f32_16x16x32_bf16 v[56:59], v[152:155], v[176:179], v[56:59]
	v_mfma_f32_16x16x32_bf16 v[52:55], v[144:147], v[184:187], v[52:55]
	v_mfma_f32_16x16x32_bf16 v[44:47], v[152:155], v[184:187], v[44:47]
	v_mfma_f32_16x16x32_bf16 v[36:39], v[144:147], v[206:209], v[36:39]
	v_mfma_f32_16x16x32_bf16 v[28:31], v[152:155], v[206:209], v[28:31]
	v_mfma_f32_16x16x32_bf16 v[20:23], v[144:147], v[214:217], v[20:23]
	v_mfma_f32_16x16x32_bf16 v[12:15], v[152:155], v[214:217], v[12:15]
	v_mfma_f32_16x16x32_bf16 v[60:63], v[148:151], v[180:183], v[60:63]
	v_mfma_f32_16x16x32_bf16 v[56:59], v[156:159], v[180:183], v[56:59]
	v_mfma_f32_16x16x32_bf16 v[52:55], v[148:151], v[188:191], v[52:55]
	v_mfma_f32_16x16x32_bf16 v[44:47], v[156:159], v[188:191], v[44:47]
	v_mfma_f32_16x16x32_bf16 v[36:39], v[148:151], v[210:213], v[36:39]
	v_mfma_f32_16x16x32_bf16 v[28:31], v[156:159], v[210:213], v[28:31]
	v_mfma_f32_16x16x32_bf16 v[20:23], v[148:151], v[218:221], v[20:23]
	v_mfma_f32_16x16x32_bf16 v[12:15], v[156:159], v[218:221], v[12:15]
	v_mfma_f32_16x16x32_bf16 v[48:51], v[160:163], v[176:179], v[48:51]
	v_mfma_f32_16x16x32_bf16 v[40:43], v[168:171], v[176:179], v[40:43]
	v_mfma_f32_16x16x32_bf16 v[32:35], v[160:163], v[184:187], v[32:35]
	v_mfma_f32_16x16x32_bf16 v[24:27], v[168:171], v[184:187], v[24:27]
	v_mfma_f32_16x16x32_bf16 v[16:19], v[160:163], v[206:209], v[16:19]
	v_mfma_f32_16x16x32_bf16 v[8:11], v[168:171], v[206:209], v[8:11]
	v_mfma_f32_16x16x32_bf16 v[4:7], v[160:163], v[214:217], v[4:7]
	v_mfma_f32_16x16x32_bf16 v[0:3], v[168:171], v[214:217], v[0:3]
	v_mfma_f32_16x16x32_bf16 v[48:51], v[164:167], v[180:183], v[48:51]
	v_mfma_f32_16x16x32_bf16 v[40:43], v[172:175], v[180:183], v[40:43]
	v_mfma_f32_16x16x32_bf16 v[32:35], v[164:167], v[188:191], v[32:35]
	v_mfma_f32_16x16x32_bf16 v[24:27], v[172:175], v[188:191], v[24:27]
	v_mfma_f32_16x16x32_bf16 v[16:19], v[164:167], v[210:213], v[16:19]
	v_mfma_f32_16x16x32_bf16 v[8:11], v[172:175], v[210:213], v[8:11]
	v_mfma_f32_16x16x32_bf16 v[4:7], v[164:167], v[218:221], v[4:7]
	v_mfma_f32_16x16x32_bf16 v[0:3], v[172:175], v[218:221], v[0:3]
	s_barrier
	s_add_i32 s37, s37, 2
	s_add_u32 s14, s14, 0x100
	s_addc_u32 s15, s15, 0
	s_add_u32 s35, s35, 0x100
	s_addc_u32 s36, s36, 0
	s_cmp_gt_u32 s37, 29
	s_cbranch_scc0 .LBB0_130
	s_and_b64 vcc, exec, s[4:5]
	s_cbranch_vccz .LBB0_133
; #define PG8_WAIT_V(n) asm volatile("s_waitcnt vmcnt(" #n ")" ::: "memory")
; #define PG8_BAR __builtin_amdgcn_s_barrier()
; __device__ __forceinline__ u32x4 pack8(const f32x4 v0, const f32x4 v1) { u32x4 w; w.x = cvt_pk_bf16(v0[0], v0[1]); w.y = cvt_pk_bf16(v0[2], v0[3]); w.z = cvt_pk_bf16(v1[0], v1[1]); w.w = cvt_pk_bf16(v1[2], v1[3]); return w; }
; template <class Epi, bool PERMA = false, bool DUAL = false, bool ALIGN_EPI = true, bool SP2 = true>
; __device__ __forceinline__ void gemm_phase(LAS unsigned char* lds, const Gemm g, const StaticOrder& S, const Epi& E) {
;     ...
;         if constexpr (ALIGN_EPI) { if (wr == 0) PG8_BAR; }
;         if constexpr (DUAL) E.dual(acc, cur, wr, wc, fr, fq, cw_); else E(acc, cur, wr, wc, fr, fq);
;         if (!has_next) break;
; #pragma unroll
;         for (int a = 0; a < 2; ++a)
; #pragma unroll
;             for (int b = 0; b < 2; ++b)
; #pragma unroll
;                 for (int m = 0; m < 4; ++m)
; #pragma unroll
;                     for (int n = 0; n < 2; ++n) acc[a][b][m][n] = (f32x4){0.f, 0.f, 0.f, 0.f};
;         cur = nxt; cA = nA; cB = nB; ++ui; cw_ = nw_;
;         if constexpr (ALIGN_EPI) { if (wr == 1) PG8_BAR; }
;     }
;     PG8_WAIT_V(0);
;     if constexpr (!ALIGN_EPI) { if (wr == 0) PG8_BAR; }
;     __device__ __forceinline__ void operator()(const f32x4 (&acc)[2][2][4][2], const Unit& u, int wr, int wc, int fr, int fq) const {
;         int colt = u.pn * BM; bf16_t* base = O; int ldc = ld;
;         if (colt >= split_col) { base = O2; ldc = ld2; colt -= split_col; }
;         const unsigned loff = (unsigned)((PERMROW ? 4 * fr : fr) * ldc + 8 * fq) * 2u;
;         char* ub = (char*)base + ((size_t)(u.pm * BM + wr * 64) * ldc + (size_t)(colt + wc * 32)) * 2;
; #pragma unroll
;         for (int ai = 0; ai < 2; ++ai)
; #pragma unroll
;             for (int m = 0; m < 4; ++m) {
; #pragma unroll
;                 for (int bj = 0; bj < 2; ++bj) *(u32x4*)(ub + ((size_t)(ai * HALF + (PERMROW ? m : m * 16)) * ldc + bj * HALF) * 2 + loff) = pack8(acc[ai][bj][m][0], acc[ai][bj][m][1]); }
;     }
.LBB0_133:
	s_lshl_b32 s7, s31, 8
	s_cmp_lt_i32 s31, 24
	s_cselect_b32 s9, 0, 0xffffe800
	s_cselect_b32 s16, s83, s61
	s_cselect_b32 s17, s82, s60
	s_cselect_b32 s18, 0x1800, s41
	s_lshl_b32 s14, s30, 8
	s_or_b32 s7, s7, s28
	s_add_i32 s14, s14, s27
	s_add_i32 s7, s7, s9
	s_mul_hi_i32 s15, s14, s18
	s_mul_i32 s14, s14, s18
	s_ashr_i32 s9, s7, 31
	s_add_u32 s14, s14, s7
	s_addc_u32 s15, s15, s9
	s_lshl_b64 s[14:15], s[14:15], 1
	v_mul_u32_u24_e32 v144, s18, v142
	s_add_u32 s14, s17, s14
	v_or_b32_e32 v144, v144, v140
	s_addc_u32 s15, s16, s15
	v_mov_b32_e32 v145, v192
	v_readlane_b32 s16, v254, 58
	v_lshl_add_u64 v[146:147], s[14:15], 0, v[144:145]
	v_readlane_b32 s17, v254, 59
	s_lshl_b32 s16, s18, 5
	v_cvt_pk_bf16_f32 v112, v112, v113
	v_cvt_pk_bf16_f32 v113, v114, v115
	v_cvt_pk_bf16_f32 v115, v106, v107
	v_cvt_pk_bf16_f32 v106, v108, v109
	s_nop 0
	v_lshl_add_u64 v[108:109], v[146:147], 0, s[16:17]
	v_cvt_pk_bf16_f32 v96, v96, v97
	v_cvt_pk_bf16_f32 v97, v98, v99
	v_cvt_pk_bf16_f32 v99, v90, v91
	v_cvt_pk_bf16_f32 v90, v92, v93
	v_lshl_add_u64 v[92:93], v[108:109], 0, s[16:17]
	v_cvt_pk_bf16_f32 v124, v124, v125
	v_cvt_pk_bf16_f32 v125, v126, v127
	v_cvt_pk_bf16_f32 v126, v120, v121
	v_cvt_pk_bf16_f32 v127, v122, v123
	global_store_dwordx4 v144, v[124:127], s[14:15]
	v_cvt_pk_bf16_f32 v114, v104, v105
	global_store_dwordx4 v144, v[112:115], s[14:15] offset:256
	v_cvt_pk_bf16_f32 v80, v80, v81
	v_cvt_pk_bf16_f32 v81, v82, v83
	v_cvt_pk_bf16_f32 v83, v74, v75
	v_cvt_pk_bf16_f32 v74, v76, v77
	v_lshl_add_u64 v[76:77], v[92:93], 0, s[16:17]
	s_mul_i32 s14, s18, 0xa0
	s_mov_b32 s15, s17
	v_cvt_pk_bf16_f32 v60, v60, v61
	v_cvt_pk_bf16_f32 v61, v62, v63
	v_cvt_pk_bf16_f32 v62, v56, v57
	v_lshl_add_u64 v[56:57], v[76:77], 0, s[14:15]
	v_cvt_pk_bf16_f32 v48, v48, v49
	v_cvt_pk_bf16_f32 v49, v50, v51
	v_cvt_pk_bf16_f32 v51, v42, v43
	v_cvt_pk_bf16_f32 v42, v44, v45
	v_lshl_add_u64 v[44:45], v[56:57], 0, s[16:17]
	s_mov_b32 s7, s17
	v_cvt_pk_bf16_f32 v32, v32, v33
	v_cvt_pk_bf16_f32 v33, v34, v35
	v_cvt_pk_bf16_f32 v35, v26, v27
	v_cvt_pk_bf16_f32 v26, v28, v29
	v_lshl_add_u64 v[28:29], v[44:45], 0, s[16:17]
	v_writelane_b32 v254, s6, 58
	v_cvt_pk_bf16_f32 v16, v16, v17
	v_cvt_pk_bf16_f32 v17, v18, v19
	v_cvt_pk_bf16_f32 v19, v10, v11
	v_cvt_pk_bf16_f32 v10, v12, v13
	v_lshl_add_u64 v[12:13], v[28:29], 0, s[16:17]
	s_nop 0
	v_writelane_b32 v254, s7, 59
	s_andn2_b64 vcc, exec, s[0:1]
	s_mov_b64 s[0:1], -1
	v_cvt_pk_bf16_f32 v104, v116, v117
	v_cvt_pk_bf16_f32 v105, v118, v119
	v_cvt_pk_bf16_f32 v107, v110, v111
	global_store_dwordx4 v[108:109], v[104:107], off
	v_cvt_pk_bf16_f32 v98, v88, v89
	global_store_dwordx4 v[108:109], v[96:99], off offset:256
	v_cvt_pk_bf16_f32 v88, v100, v101
	v_cvt_pk_bf16_f32 v89, v102, v103
	v_cvt_pk_bf16_f32 v91, v94, v95
	global_store_dwordx4 v[92:93], v[88:91], off
	v_cvt_pk_bf16_f32 v82, v72, v73
	global_store_dwordx4 v[92:93], v[80:83], off offset:256
	v_cvt_pk_bf16_f32 v72, v84, v85
	v_cvt_pk_bf16_f32 v73, v86, v87
	v_cvt_pk_bf16_f32 v75, v78, v79
	global_store_dwordx4 v[76:77], v[72:75], off
	v_cvt_pk_bf16_f32 v68, v68, v69
	v_cvt_pk_bf16_f32 v69, v70, v71
	v_cvt_pk_bf16_f32 v70, v64, v65
	v_cvt_pk_bf16_f32 v71, v66, v67
	global_store_dwordx4 v[76:77], v[68:71], off offset:256
	v_cvt_pk_bf16_f32 v63, v58, v59
	global_store_dwordx4 v[56:57], v[60:63], off
	v_cvt_pk_bf16_f32 v50, v40, v41
	global_store_dwordx4 v[56:57], v[48:51], off offset:256
	v_cvt_pk_bf16_f32 v40, v52, v53
	v_cvt_pk_bf16_f32 v41, v54, v55
	v_cvt_pk_bf16_f32 v43, v46, v47
	global_store_dwordx4 v[44:45], v[40:43], off
	v_cvt_pk_bf16_f32 v34, v24, v25
	global_store_dwordx4 v[44:45], v[32:35], off offset:256
	v_cvt_pk_bf16_f32 v24, v36, v37
	v_cvt_pk_bf16_f32 v25, v38, v39
	v_cvt_pk_bf16_f32 v27, v30, v31
	global_store_dwordx4 v[28:29], v[24:27], off
	v_cvt_pk_bf16_f32 v18, v8, v9
	global_store_dwordx4 v[28:29], v[16:19], off offset:256
	v_cvt_pk_bf16_f32 v8, v20, v21
	v_cvt_pk_bf16_f32 v9, v22, v23
	v_cvt_pk_bf16_f32 v11, v14, v15
	global_store_dwordx4 v[12:13], v[8:11], off
	v_cvt_pk_bf16_f32 v4, v4, v5
	v_cvt_pk_bf16_f32 v5, v6, v7
	v_cvt_pk_bf16_f32 v6, v0, v1
	v_cvt_pk_bf16_f32 v7, v2, v3
	global_store_dwordx4 v[12:13], v[4:7], off offset:256
	s_cbranch_vccnz .LBB0_126
	s_andn2_b64 vcc, exec, s[2:3]
	s_cbranch_vccnz .LBB0_125
	s_branch .LBB0_125
.LBB0_136:
	s_waitcnt vmcnt(0)
	s_and_b64 vcc, exec, s[4:5]
	s_cbranch_vccz .Lp1_noalign_end
	s_barrier
.Lp1_noalign_end:
	s_barrier
